# merge kernel: LDS-DMA loads of a step spread over every other MFMA slot of the second half-step
# speedup vs baseline: 1.1209x; 1.0072x over previous
.Lgm_branch:
	s_waitcnt lgkmcnt(0)
	v_mfma_f32_16x16x32_bf16 v[2:5], v[90:93], v[106:109], 0
	ds_read_b128 v[144:147], v142 offset:1024
	v_mfma_f32_16x16x32_bf16 v[6:9], v[94:97], v[106:109], 0
	ds_read_b128 v[148:151], v142 offset:3072
	v_mfma_f32_16x16x32_bf16 v[10:13], v[98:101], v[106:109], 0
	ds_read_b128 v[152:155], v142 offset:5120
	v_mfma_f32_16x16x32_bf16 v[14:17], v[102:105], v[106:109], 0
	ds_read_b128 v[156:159], v142 offset:7168
	v_mfma_f32_16x16x32_bf16 v[18:21], v[90:93], v[110:113], 0
	ds_read_b128 v[160:163], v141 offset:1024
	v_mfma_f32_16x16x32_bf16 v[22:25], v[94:97], v[110:113], 0
	ds_read_b128 v[164:167], v141 offset:3072
	v_mfma_f32_16x16x32_bf16 v[26:29], v[98:101], v[110:113], 0
	ds_read_b128 v[168:171], v141 offset:5120
	v_mfma_f32_16x16x32_bf16 v[30:33], v[102:105], v[110:113], 0
	ds_read_b128 v[172:175], v141 offset:7168
	v_mfma_f32_16x16x32_bf16 v[34:37], v[90:93], v[114:117], 0
	v_mfma_f32_16x16x32_bf16 v[38:41], v[94:97], v[114:117], 0
	v_mfma_f32_16x16x32_bf16 v[42:45], v[98:101], v[114:117], 0
	v_mfma_f32_16x16x32_bf16 v[46:49], v[102:105], v[114:117], 0
	v_mfma_f32_16x16x32_bf16 v[50:53], v[90:93], v[118:121], 0
	v_mfma_f32_16x16x32_bf16 v[54:57], v[94:97], v[118:121], 0
	v_mfma_f32_16x16x32_bf16 v[58:61], v[98:101], v[118:121], 0
	v_mfma_f32_16x16x32_bf16 v[62:65], v[102:105], v[118:121], 0
	s_waitcnt vmcnt(0) lgkmcnt(0)
	s_barrier
	v_mfma_f32_16x16x32_bf16 v[2:5], v[144:147], v[160:163], v[2:5]
	ds_read_b128 v[90:93], v142 offset:32768
	s_add_u32 m0, s22, 0x0
	v_mov_b32_e32 v177, v136
	global_load_lds_dwordx4 v177, s[6:7]
	v_mfma_f32_16x16x32_bf16 v[6:9], v[148:151], v[160:163], v[6:9]
	ds_read_b128 v[94:97], v142 offset:34816
	v_mfma_f32_16x16x32_bf16 v[10:13], v[152:155], v[160:163], v[10:13]
	ds_read_b128 v[98:101], v142 offset:36864
	s_add_u32 m0, s22, 0x400
	v_add_u32_e32 v178, 0x40, v136
	global_load_lds_dwordx4 v178, s[6:7]
	v_mfma_f32_16x16x32_bf16 v[14:17], v[156:159], v[160:163], v[14:17]
	ds_read_b128 v[102:105], v142 offset:38912
	v_mfma_f32_16x16x32_bf16 v[18:21], v[144:147], v[164:167], v[18:21]
	ds_read_b128 v[106:109], v141 offset:32768
	s_add_u32 m0, s22, 0x800
	v_add_u32_e32 v177, 0x8000, v136
	global_load_lds_dwordx4 v177, s[6:7]
	v_mfma_f32_16x16x32_bf16 v[22:25], v[148:151], v[164:167], v[22:25]
	ds_read_b128 v[110:113], v141 offset:34816
	v_mfma_f32_16x16x32_bf16 v[26:29], v[152:155], v[164:167], v[26:29]
	ds_read_b128 v[114:117], v141 offset:36864
	s_add_u32 m0, s22, 0xc00
	v_add_u32_e32 v178, 0x8040, v136
	global_load_lds_dwordx4 v178, s[6:7]
	v_mfma_f32_16x16x32_bf16 v[30:33], v[156:159], v[164:167], v[30:33]
	ds_read_b128 v[118:121], v141 offset:38912
	v_mfma_f32_16x16x32_bf16 v[34:37], v[144:147], v[168:171], v[34:37]
	s_add_u32 m0, s22, 0x4000
	v_mov_b32_e32 v177, v137
	global_load_lds_dwordx4 v177, s[8:9]
	v_mfma_f32_16x16x32_bf16 v[38:41], v[148:151], v[168:171], v[38:41]
	v_mfma_f32_16x16x32_bf16 v[42:45], v[152:155], v[168:171], v[42:45]
	s_add_u32 m0, s22, 0x4400
	v_add_u32_e32 v178, 0x40, v137
	global_load_lds_dwordx4 v178, s[8:9]
	v_mfma_f32_16x16x32_bf16 v[46:49], v[156:159], v[168:171], v[46:49]
	v_mfma_f32_16x16x32_bf16 v[50:53], v[144:147], v[172:175], v[50:53]
	s_add_u32 m0, s22, 0x4800
	v_add_u32_e32 v177, 0x2000, v137
	global_load_lds_dwordx4 v177, s[8:9]
	v_mfma_f32_16x16x32_bf16 v[54:57], v[148:151], v[172:175], v[54:57]
	v_mfma_f32_16x16x32_bf16 v[58:61], v[152:155], v[172:175], v[58:61]
	s_add_u32 m0, s22, 0x4c00
	v_add_u32_e32 v178, 0x2040, v137
	global_load_lds_dwordx4 v178, s[8:9]
	v_mfma_f32_16x16x32_bf16 v[62:65], v[156:159], v[172:175], v[62:65]
	v_add_u32_e32 v136, 0x80, v136
	v_add_u32_e32 v137, 0x80, v137
	s_waitcnt lgkmcnt(0)
	v_mfma_f32_16x16x32_bf16 v[2:5], v[90:93], v[106:109], v[2:5]
	ds_read_b128 v[144:147], v142 offset:33792
	v_mfma_f32_16x16x32_bf16 v[6:9], v[94:97], v[106:109], v[6:9]
	ds_read_b128 v[148:151], v142 offset:35840
	v_mfma_f32_16x16x32_bf16 v[10:13], v[98:101], v[106:109], v[10:13]
	ds_read_b128 v[152:155], v142 offset:37888
	v_mfma_f32_16x16x32_bf16 v[14:17], v[102:105], v[106:109], v[14:17]
	ds_read_b128 v[156:159], v142 offset:39936
	v_mfma_f32_16x16x32_bf16 v[18:21], v[90:93], v[110:113], v[18:21]
	ds_read_b128 v[160:163], v141 offset:33792
	v_mfma_f32_16x16x32_bf16 v[22:25], v[94:97], v[110:113], v[22:25]
	ds_read_b128 v[164:167], v141 offset:35840
	v_mfma_f32_16x16x32_bf16 v[26:29], v[98:101], v[110:113], v[26:29]
	ds_read_b128 v[168:171], v141 offset:37888
	v_mfma_f32_16x16x32_bf16 v[30:33], v[102:105], v[110:113], v[30:33]
	ds_read_b128 v[172:175], v141 offset:39936
	v_mfma_f32_16x16x32_bf16 v[34:37], v[90:93], v[114:117], v[34:37]
	v_mfma_f32_16x16x32_bf16 v[38:41], v[94:97], v[114:117], v[38:41]
	v_mfma_f32_16x16x32_bf16 v[42:45], v[98:101], v[114:117], v[42:45]
	v_mfma_f32_16x16x32_bf16 v[46:49], v[102:105], v[114:117], v[46:49]
	v_mfma_f32_16x16x32_bf16 v[50:53], v[90:93], v[118:121], v[50:53]
	v_mfma_f32_16x16x32_bf16 v[54:57], v[94:97], v[118:121], v[54:57]
	v_mfma_f32_16x16x32_bf16 v[58:61], v[98:101], v[118:121], v[58:61]
	v_mfma_f32_16x16x32_bf16 v[62:65], v[102:105], v[118:121], v[62:65]
	s_waitcnt vmcnt(0) lgkmcnt(0)
	s_barrier
	v_mfma_f32_16x16x32_bf16 v[2:5], v[144:147], v[160:163], v[2:5]
	ds_read_b128 v[90:93], v142
	s_add_u32 m0, s22, 0x8000
	v_mov_b32_e32 v177, v136
	global_load_lds_dwordx4 v177, s[6:7]
	v_mfma_f32_16x16x32_bf16 v[6:9], v[148:151], v[160:163], v[6:9]
	ds_read_b128 v[94:97], v142 offset:2048
	v_mfma_f32_16x16x32_bf16 v[10:13], v[152:155], v[160:163], v[10:13]
	ds_read_b128 v[98:101], v142 offset:4096
	s_add_u32 m0, s22, 0x8400
	v_add_u32_e32 v178, 0x40, v136
	global_load_lds_dwordx4 v178, s[6:7]
	v_mfma_f32_16x16x32_bf16 v[14:17], v[156:159], v[160:163], v[14:17]
	ds_read_b128 v[102:105], v142 offset:6144
	v_mfma_f32_16x16x32_bf16 v[18:21], v[144:147], v[164:167], v[18:21]
	ds_read_b128 v[106:109], v141
	s_add_u32 m0, s22, 0x8800
	v_add_u32_e32 v177, 0x8000, v136
	global_load_lds_dwordx4 v177, s[6:7]
	v_mfma_f32_16x16x32_bf16 v[22:25], v[148:151], v[164:167], v[22:25]
	ds_read_b128 v[110:113], v141 offset:2048
	v_mfma_f32_16x16x32_bf16 v[26:29], v[152:155], v[164:167], v[26:29]
	ds_read_b128 v[114:117], v141 offset:4096
	s_add_u32 m0, s22, 0x8c00
	v_add_u32_e32 v178, 0x8040, v136
	global_load_lds_dwordx4 v178, s[6:7]
	v_mfma_f32_16x16x32_bf16 v[30:33], v[156:159], v[164:167], v[30:33]
	ds_read_b128 v[118:121], v141 offset:6144
	v_mfma_f32_16x16x32_bf16 v[34:37], v[144:147], v[168:171], v[34:37]
	s_add_u32 m0, s22, 0xc000
	v_mov_b32_e32 v177, v137
	global_load_lds_dwordx4 v177, s[8:9]
	v_mfma_f32_16x16x32_bf16 v[38:41], v[148:151], v[168:171], v[38:41]
	v_mfma_f32_16x16x32_bf16 v[42:45], v[152:155], v[168:171], v[42:45]
	s_add_u32 m0, s22, 0xc400
	v_add_u32_e32 v178, 0x40, v137
	global_load_lds_dwordx4 v178, s[8:9]
	v_mfma_f32_16x16x32_bf16 v[46:49], v[156:159], v[168:171], v[46:49]
	v_mfma_f32_16x16x32_bf16 v[50:53], v[144:147], v[172:175], v[50:53]
	s_add_u32 m0, s22, 0xc800
	v_add_u32_e32 v177, 0x2000, v137
	global_load_lds_dwordx4 v177, s[8:9]
	v_mfma_f32_16x16x32_bf16 v[54:57], v[148:151], v[172:175], v[54:57]
	v_mfma_f32_16x16x32_bf16 v[58:61], v[152:155], v[172:175], v[58:61]
	s_add_u32 m0, s22, 0xcc00
	v_add_u32_e32 v178, 0x2040, v137
	global_load_lds_dwordx4 v178, s[8:9]
	v_mfma_f32_16x16x32_bf16 v[62:65], v[156:159], v[172:175], v[62:65]
	v_add_u32_e32 v136, 0x80, v136
	v_add_u32_e32 v137, 0x80, v137
	v_mov_b32_e32 v138, v134
	v_mov_b32_e32 v139, v140
	v_add_u32_e32 v140, 0x200000, v140
	s_waitcnt lgkmcnt(0)
	v_mfma_f32_16x16x32_bf16 v[2:5], v[90:93], v[106:109], v[2:5]
	ds_read_b128 v[144:147], v142 offset:1024
	v_mfma_f32_16x16x32_bf16 v[6:9], v[94:97], v[106:109], v[6:9]
	ds_read_b128 v[148:151], v142 offset:3072
	v_mfma_f32_16x16x32_bf16 v[10:13], v[98:101], v[106:109], v[10:13]
	ds_read_b128 v[152:155], v142 offset:5120
	v_mfma_f32_16x16x32_bf16 v[14:17], v[102:105], v[106:109], v[14:17]
	ds_read_b128 v[156:159], v142 offset:7168
	v_mfma_f32_16x16x32_bf16 v[18:21], v[90:93], v[110:113], v[18:21]
	ds_read_b128 v[160:163], v141 offset:1024
	v_mfma_f32_16x16x32_bf16 v[22:25], v[94:97], v[110:113], v[22:25]
	ds_read_b128 v[164:167], v141 offset:3072
	v_mfma_f32_16x16x32_bf16 v[26:29], v[98:101], v[110:113], v[26:29]
	ds_read_b128 v[168:171], v141 offset:5120
	v_mfma_f32_16x16x32_bf16 v[30:33], v[102:105], v[110:113], v[30:33]
	ds_read_b128 v[172:175], v141 offset:7168
	v_mfma_f32_16x16x32_bf16 v[34:37], v[90:93], v[114:117], v[34:37]
	v_mfma_f32_16x16x32_bf16 v[38:41], v[94:97], v[114:117], v[38:41]
	v_mfma_f32_16x16x32_bf16 v[42:45], v[98:101], v[114:117], v[42:45]
	v_mfma_f32_16x16x32_bf16 v[46:49], v[102:105], v[114:117], v[46:49]
	v_mfma_f32_16x16x32_bf16 v[50:53], v[90:93], v[118:121], v[50:53]
	v_mfma_f32_16x16x32_bf16 v[54:57], v[94:97], v[118:121], v[54:57]
	v_mfma_f32_16x16x32_bf16 v[58:61], v[98:101], v[118:121], v[58:61]
	v_mfma_f32_16x16x32_bf16 v[62:65], v[102:105], v[118:121], v[62:65]
	s_waitcnt vmcnt(0) lgkmcnt(0)
	s_barrier
	v_mfma_f32_16x16x32_bf16 v[2:5], v[144:147], v[160:163], v[2:5]
	ds_read_b128 v[90:93], v142 offset:32768
	s_add_u32 m0, s22, 0x0
	v_mov_b32_e32 v177, v138
	global_load_lds_dwordx4 v177, s[18:19]
	v_mfma_f32_16x16x32_bf16 v[6:9], v[148:151], v[160:163], v[6:9]
	ds_read_b128 v[94:97], v142 offset:34816
	v_mfma_f32_16x16x32_bf16 v[10:13], v[152:155], v[160:163], v[10:13]
	ds_read_b128 v[98:101], v142 offset:36864
	s_add_u32 m0, s22, 0x400
	v_add_u32_e32 v178, 0x40, v138
	global_load_lds_dwordx4 v178, s[18:19]
	v_mfma_f32_16x16x32_bf16 v[14:17], v[156:159], v[160:163], v[14:17]
	ds_read_b128 v[102:105], v142 offset:38912
	v_mfma_f32_16x16x32_bf16 v[18:21], v[144:147], v[164:167], v[18:21]
	ds_read_b128 v[106:109], v141 offset:32768
	s_add_u32 m0, s22, 0x800
	v_add_u32_e32 v177, 0x8000, v138
	global_load_lds_dwordx4 v177, s[18:19]
	v_mfma_f32_16x16x32_bf16 v[22:25], v[148:151], v[164:167], v[22:25]
	ds_read_b128 v[110:113], v141 offset:34816
	v_mfma_f32_16x16x32_bf16 v[26:29], v[152:155], v[164:167], v[26:29]
	ds_read_b128 v[114:117], v141 offset:36864
	s_add_u32 m0, s22, 0xc00
	v_add_u32_e32 v178, 0x8040, v138
	global_load_lds_dwordx4 v178, s[18:19]
	v_mfma_f32_16x16x32_bf16 v[30:33], v[156:159], v[164:167], v[30:33]
	ds_read_b128 v[118:121], v141 offset:38912
	v_mfma_f32_16x16x32_bf16 v[34:37], v[144:147], v[168:171], v[34:37]
	s_add_u32 m0, s22, 0x4000
	v_mov_b32_e32 v177, v139
	global_load_lds_dwordx4 v177, s[20:21]
	v_mfma_f32_16x16x32_bf16 v[38:41], v[148:151], v[168:171], v[38:41]
	v_mfma_f32_16x16x32_bf16 v[42:45], v[152:155], v[168:171], v[42:45]
	s_add_u32 m0, s22, 0x4400
	v_add_u32_e32 v178, 0x40, v139
	global_load_lds_dwordx4 v178, s[20:21]
	v_mfma_f32_16x16x32_bf16 v[46:49], v[156:159], v[168:171], v[46:49]
	v_mfma_f32_16x16x32_bf16 v[50:53], v[144:147], v[172:175], v[50:53]
	s_add_u32 m0, s22, 0x4800
	v_add_u32_e32 v177, 0x8000, v139
	global_load_lds_dwordx4 v177, s[20:21]
	v_mfma_f32_16x16x32_bf16 v[54:57], v[148:151], v[172:175], v[54:57]
	v_mfma_f32_16x16x32_bf16 v[58:61], v[152:155], v[172:175], v[58:61]
	s_add_u32 m0, s22, 0x4c00
	v_add_u32_e32 v178, 0x8040, v139
	global_load_lds_dwordx4 v178, s[20:21]
	v_mfma_f32_16x16x32_bf16 v[62:65], v[156:159], v[172:175], v[62:65]
	v_add_u32_e32 v138, 0x80, v138
	v_add_u32_e32 v139, 0x80, v139
	s_waitcnt lgkmcnt(0)
	v_mfma_f32_16x16x32_bf16 v[2:5], v[90:93], v[106:109], v[2:5]
	ds_read_b128 v[144:147], v142 offset:33792
	v_mfma_f32_16x16x32_bf16 v[6:9], v[94:97], v[106:109], v[6:9]
	ds_read_b128 v[148:151], v142 offset:35840
	v_mfma_f32_16x16x32_bf16 v[10:13], v[98:101], v[106:109], v[10:13]
	ds_read_b128 v[152:155], v142 offset:37888
	v_mfma_f32_16x16x32_bf16 v[14:17], v[102:105], v[106:109], v[14:17]
	ds_read_b128 v[156:159], v142 offset:39936
	v_mfma_f32_16x16x32_bf16 v[18:21], v[90:93], v[110:113], v[18:21]
	ds_read_b128 v[160:163], v141 offset:33792
	v_mfma_f32_16x16x32_bf16 v[22:25], v[94:97], v[110:113], v[22:25]
	ds_read_b128 v[164:167], v141 offset:35840
	v_mfma_f32_16x16x32_bf16 v[26:29], v[98:101], v[110:113], v[26:29]
	ds_read_b128 v[168:171], v141 offset:37888
	v_mfma_f32_16x16x32_bf16 v[30:33], v[102:105], v[110:113], v[30:33]
	ds_read_b128 v[172:175], v141 offset:39936
	v_mfma_f32_16x16x32_bf16 v[34:37], v[90:93], v[114:117], v[34:37]
	v_mfma_f32_16x16x32_bf16 v[38:41], v[94:97], v[114:117], v[38:41]
	v_mfma_f32_16x16x32_bf16 v[42:45], v[98:101], v[114:117], v[42:45]
	v_mfma_f32_16x16x32_bf16 v[46:49], v[102:105], v[114:117], v[46:49]
	v_mfma_f32_16x16x32_bf16 v[50:53], v[90:93], v[118:121], v[50:53]
	v_mfma_f32_16x16x32_bf16 v[54:57], v[94:97], v[118:121], v[54:57]
	v_mfma_f32_16x16x32_bf16 v[58:61], v[98:101], v[118:121], v[58:61]
	v_mfma_f32_16x16x32_bf16 v[62:65], v[102:105], v[118:121], v[62:65]
	s_waitcnt vmcnt(0) lgkmcnt(0)
	s_barrier
	v_mfma_f32_16x16x32_bf16 v[2:5], v[144:147], v[160:163], v[2:5]
	ds_read_b128 v[90:93], v142
	s_add_u32 m0, s22, 0x8000
	v_mov_b32_e32 v177, v138
	global_load_lds_dwordx4 v177, s[18:19]
	v_mfma_f32_16x16x32_bf16 v[6:9], v[148:151], v[160:163], v[6:9]
	ds_read_b128 v[94:97], v142 offset:2048
	v_mfma_f32_16x16x32_bf16 v[10:13], v[152:155], v[160:163], v[10:13]
	ds_read_b128 v[98:101], v142 offset:4096
	s_add_u32 m0, s22, 0x8400
	v_add_u32_e32 v178, 0x40, v138
	global_load_lds_dwordx4 v178, s[18:19]
	v_mfma_f32_16x16x32_bf16 v[14:17], v[156:159], v[160:163], v[14:17]
	ds_read_b128 v[102:105], v142 offset:6144
	v_mfma_f32_16x16x32_bf16 v[18:21], v[144:147], v[164:167], v[18:21]
	ds_read_b128 v[106:109], v141
	s_add_u32 m0, s22, 0x8800
	v_add_u32_e32 v177, 0x8000, v138
	global_load_lds_dwordx4 v177, s[18:19]
	v_mfma_f32_16x16x32_bf16 v[22:25], v[148:151], v[164:167], v[22:25]
	ds_read_b128 v[110:113], v141 offset:2048
	v_mfma_f32_16x16x32_bf16 v[26:29], v[152:155], v[164:167], v[26:29]
	ds_read_b128 v[114:117], v141 offset:4096
	s_add_u32 m0, s22, 0x8c00
	v_add_u32_e32 v178, 0x8040, v138
	global_load_lds_dwordx4 v178, s[18:19]
	v_mfma_f32_16x16x32_bf16 v[30:33], v[156:159], v[164:167], v[30:33]
	ds_read_b128 v[118:121], v141 offset:6144
	v_mfma_f32_16x16x32_bf16 v[34:37], v[144:147], v[168:171], v[34:37]
	s_add_u32 m0, s22, 0xc000
	v_mov_b32_e32 v177, v139
	global_load_lds_dwordx4 v177, s[20:21]
	v_mfma_f32_16x16x32_bf16 v[38:41], v[148:151], v[168:171], v[38:41]
	v_mfma_f32_16x16x32_bf16 v[42:45], v[152:155], v[168:171], v[42:45]
	s_add_u32 m0, s22, 0xc400
	v_add_u32_e32 v178, 0x40, v139
	global_load_lds_dwordx4 v178, s[20:21]
	v_mfma_f32_16x16x32_bf16 v[46:49], v[156:159], v[168:171], v[46:49]
	v_mfma_f32_16x16x32_bf16 v[50:53], v[144:147], v[172:175], v[50:53]
	s_add_u32 m0, s22, 0xc800
	v_add_u32_e32 v177, 0x8000, v139
	global_load_lds_dwordx4 v177, s[20:21]
	v_mfma_f32_16x16x32_bf16 v[54:57], v[148:151], v[172:175], v[54:57]
	v_mfma_f32_16x16x32_bf16 v[58:61], v[152:155], v[172:175], v[58:61]
	s_add_u32 m0, s22, 0xcc00
	v_add_u32_e32 v178, 0x8040, v139
	global_load_lds_dwordx4 v178, s[20:21]
	v_mfma_f32_16x16x32_bf16 v[62:65], v[156:159], v[172:175], v[62:65]
	v_add_u32_e32 v138, 0x80, v138
	v_add_u32_e32 v139, 0x80, v139
	v_cvt_pk_bf16_f32 v196, v2, v3
	v_cvt_pk_bf16_f32 v197, v4, v5
	v_cvt_pk_bf16_f32 v198, v6, v7
	v_cvt_pk_bf16_f32 v199, v8, v9
	v_cvt_pk_bf16_f32 v200, v10, v11
	v_cvt_pk_bf16_f32 v201, v12, v13
	v_cvt_pk_bf16_f32 v202, v14, v15
	v_cvt_pk_bf16_f32 v203, v16, v17
	v_cvt_pk_bf16_f32 v204, v18, v19
	v_cvt_pk_bf16_f32 v205, v20, v21
	v_cvt_pk_bf16_f32 v206, v22, v23
	v_cvt_pk_bf16_f32 v207, v24, v25
	v_cvt_pk_bf16_f32 v212, v26, v27
	v_cvt_pk_bf16_f32 v213, v28, v29
	v_cvt_pk_bf16_f32 v214, v30, v31
	v_cvt_pk_bf16_f32 v215, v32, v33
	v_cvt_pk_bf16_f32 v216, v34, v35
	v_cvt_pk_bf16_f32 v217, v36, v37
	v_cvt_pk_bf16_f32 v218, v38, v39
	v_cvt_pk_bf16_f32 v219, v40, v41
	v_cvt_pk_bf16_f32 v220, v42, v43
	v_cvt_pk_bf16_f32 v221, v44, v45
	v_cvt_pk_bf16_f32 v222, v46, v47
	v_cvt_pk_bf16_f32 v223, v48, v49
	v_cvt_pk_bf16_f32 v224, v50, v51
	v_cvt_pk_bf16_f32 v225, v52, v53
	v_cvt_pk_bf16_f32 v226, v54, v55
	v_cvt_pk_bf16_f32 v227, v56, v57
	v_cvt_pk_bf16_f32 v228, v58, v59
	v_cvt_pk_bf16_f32 v229, v60, v61
	v_cvt_pk_bf16_f32 v230, v62, v63
	v_cvt_pk_bf16_f32 v231, v64, v65
	s_waitcnt lgkmcnt(0)
	v_mfma_f32_16x16x32_bf16 v[2:5], v[90:93], v[106:109], 0
	ds_read_b128 v[144:147], v142 offset:1024
	v_mfma_f32_16x16x32_bf16 v[6:9], v[94:97], v[106:109], 0
	ds_read_b128 v[148:151], v142 offset:3072
	v_mfma_f32_16x16x32_bf16 v[10:13], v[98:101], v[106:109], 0
	ds_read_b128 v[152:155], v142 offset:5120
	v_mfma_f32_16x16x32_bf16 v[14:17], v[102:105], v[106:109], 0
	ds_read_b128 v[156:159], v142 offset:7168
	v_mfma_f32_16x16x32_bf16 v[18:21], v[90:93], v[110:113], 0
	ds_read_b128 v[160:163], v141 offset:1024
	v_mfma_f32_16x16x32_bf16 v[22:25], v[94:97], v[110:113], 0
	ds_read_b128 v[164:167], v141 offset:3072
	v_mfma_f32_16x16x32_bf16 v[26:29], v[98:101], v[110:113], 0
	ds_read_b128 v[168:171], v141 offset:5120
	v_mfma_f32_16x16x32_bf16 v[30:33], v[102:105], v[110:113], 0
	ds_read_b128 v[172:175], v141 offset:7168
	v_mfma_f32_16x16x32_bf16 v[34:37], v[90:93], v[114:117], 0
	v_mfma_f32_16x16x32_bf16 v[38:41], v[94:97], v[114:117], 0
	v_mfma_f32_16x16x32_bf16 v[42:45], v[98:101], v[114:117], 0
	v_mfma_f32_16x16x32_bf16 v[46:49], v[102:105], v[114:117], 0
	v_mfma_f32_16x16x32_bf16 v[50:53], v[90:93], v[118:121], 0
	v_mfma_f32_16x16x32_bf16 v[54:57], v[94:97], v[118:121], 0
	v_mfma_f32_16x16x32_bf16 v[58:61], v[98:101], v[118:121], 0
	v_mfma_f32_16x16x32_bf16 v[62:65], v[102:105], v[118:121], 0
	s_waitcnt vmcnt(0) lgkmcnt(0)
	s_barrier
	v_mfma_f32_16x16x32_bf16 v[2:5], v[144:147], v[160:163], v[2:5]
	ds_read_b128 v[90:93], v142 offset:32768
	s_add_u32 m0, s22, 0x0
	v_mov_b32_e32 v177, v138
	global_load_lds_dwordx4 v177, s[18:19]
	v_mfma_f32_16x16x32_bf16 v[6:9], v[148:151], v[160:163], v[6:9]
	ds_read_b128 v[94:97], v142 offset:34816
	v_mfma_f32_16x16x32_bf16 v[10:13], v[152:155], v[160:163], v[10:13]
	ds_read_b128 v[98:101], v142 offset:36864
	s_add_u32 m0, s22, 0x400
	v_add_u32_e32 v178, 0x40, v138
	global_load_lds_dwordx4 v178, s[18:19]
	v_mfma_f32_16x16x32_bf16 v[14:17], v[156:159], v[160:163], v[14:17]
	ds_read_b128 v[102:105], v142 offset:38912
	v_mfma_f32_16x16x32_bf16 v[18:21], v[144:147], v[164:167], v[18:21]
	ds_read_b128 v[106:109], v141 offset:32768
	s_add_u32 m0, s22, 0x800
	v_add_u32_e32 v177, 0x8000, v138
	global_load_lds_dwordx4 v177, s[18:19]
	v_mfma_f32_16x16x32_bf16 v[22:25], v[148:151], v[164:167], v[22:25]
	ds_read_b128 v[110:113], v141 offset:34816
	v_mfma_f32_16x16x32_bf16 v[26:29], v[152:155], v[164:167], v[26:29]
	ds_read_b128 v[114:117], v141 offset:36864
	s_add_u32 m0, s22, 0xc00
	v_add_u32_e32 v178, 0x8040, v138
	global_load_lds_dwordx4 v178, s[18:19]
	v_mfma_f32_16x16x32_bf16 v[30:33], v[156:159], v[164:167], v[30:33]
	ds_read_b128 v[118:121], v141 offset:38912
	v_mfma_f32_16x16x32_bf16 v[34:37], v[144:147], v[168:171], v[34:37]
	s_add_u32 m0, s22, 0x4000
	v_mov_b32_e32 v177, v139
	global_load_lds_dwordx4 v177, s[20:21]
	v_mfma_f32_16x16x32_bf16 v[38:41], v[148:151], v[168:171], v[38:41]
	v_mfma_f32_16x16x32_bf16 v[42:45], v[152:155], v[168:171], v[42:45]
	s_add_u32 m0, s22, 0x4400
	v_add_u32_e32 v178, 0x40, v139
	global_load_lds_dwordx4 v178, s[20:21]
	v_mfma_f32_16x16x32_bf16 v[46:49], v[156:159], v[168:171], v[46:49]
	v_mfma_f32_16x16x32_bf16 v[50:53], v[144:147], v[172:175], v[50:53]
	s_add_u32 m0, s22, 0x4800
	v_add_u32_e32 v177, 0x8000, v139
	global_load_lds_dwordx4 v177, s[20:21]
	v_mfma_f32_16x16x32_bf16 v[54:57], v[148:151], v[172:175], v[54:57]
	v_mfma_f32_16x16x32_bf16 v[58:61], v[152:155], v[172:175], v[58:61]
	s_add_u32 m0, s22, 0x4c00
	v_add_u32_e32 v178, 0x8040, v139
	global_load_lds_dwordx4 v178, s[20:21]
	v_mfma_f32_16x16x32_bf16 v[62:65], v[156:159], v[172:175], v[62:65]
	v_add_u32_e32 v138, 0x80, v138
	v_add_u32_e32 v139, 0x80, v139
	s_waitcnt lgkmcnt(0)
	v_mfma_f32_16x16x32_bf16 v[2:5], v[90:93], v[106:109], v[2:5]
	ds_read_b128 v[144:147], v142 offset:33792
	v_mfma_f32_16x16x32_bf16 v[6:9], v[94:97], v[106:109], v[6:9]
	ds_read_b128 v[148:151], v142 offset:35840
	v_mfma_f32_16x16x32_bf16 v[10:13], v[98:101], v[106:109], v[10:13]
	ds_read_b128 v[152:155], v142 offset:37888
	v_mfma_f32_16x16x32_bf16 v[14:17], v[102:105], v[106:109], v[14:17]
	ds_read_b128 v[156:159], v142 offset:39936
	v_mfma_f32_16x16x32_bf16 v[18:21], v[90:93], v[110:113], v[18:21]
	ds_read_b128 v[160:163], v141 offset:33792
	v_mfma_f32_16x16x32_bf16 v[22:25], v[94:97], v[110:113], v[22:25]
	ds_read_b128 v[164:167], v141 offset:35840
	v_mfma_f32_16x16x32_bf16 v[26:29], v[98:101], v[110:113], v[26:29]
	ds_read_b128 v[168:171], v141 offset:37888
	v_mfma_f32_16x16x32_bf16 v[30:33], v[102:105], v[110:113], v[30:33]
	ds_read_b128 v[172:175], v141 offset:39936
	v_mfma_f32_16x16x32_bf16 v[34:37], v[90:93], v[114:117], v[34:37]
	v_mfma_f32_16x16x32_bf16 v[38:41], v[94:97], v[114:117], v[38:41]
	v_mfma_f32_16x16x32_bf16 v[42:45], v[98:101], v[114:117], v[42:45]
	v_mfma_f32_16x16x32_bf16 v[46:49], v[102:105], v[114:117], v[46:49]
	v_mfma_f32_16x16x32_bf16 v[50:53], v[90:93], v[118:121], v[50:53]
	v_mfma_f32_16x16x32_bf16 v[54:57], v[94:97], v[118:121], v[54:57]
	v_mfma_f32_16x16x32_bf16 v[58:61], v[98:101], v[118:121], v[58:61]
	v_mfma_f32_16x16x32_bf16 v[62:65], v[102:105], v[118:121], v[62:65]
	s_waitcnt vmcnt(0) lgkmcnt(0)
	s_barrier
	v_mfma_f32_16x16x32_bf16 v[2:5], v[144:147], v[160:163], v[2:5]
	ds_read_b128 v[90:93], v142
	s_add_u32 m0, s22, 0x8000
	v_mov_b32_e32 v177, v138
	global_load_lds_dwordx4 v177, s[18:19]
	v_mfma_f32_16x16x32_bf16 v[6:9], v[148:151], v[160:163], v[6:9]
	ds_read_b128 v[94:97], v142 offset:2048
	v_mfma_f32_16x16x32_bf16 v[10:13], v[152:155], v[160:163], v[10:13]
	ds_read_b128 v[98:101], v142 offset:4096
	s_add_u32 m0, s22, 0x8400
	v_add_u32_e32 v178, 0x40, v138
	global_load_lds_dwordx4 v178, s[18:19]
	v_mfma_f32_16x16x32_bf16 v[14:17], v[156:159], v[160:163], v[14:17]
	ds_read_b128 v[102:105], v142 offset:6144
	v_mfma_f32_16x16x32_bf16 v[18:21], v[144:147], v[164:167], v[18:21]
	ds_read_b128 v[106:109], v141
	s_add_u32 m0, s22, 0x8800
	v_add_u32_e32 v177, 0x8000, v138
	global_load_lds_dwordx4 v177, s[18:19]
	v_mfma_f32_16x16x32_bf16 v[22:25], v[148:151], v[164:167], v[22:25]
	ds_read_b128 v[110:113], v141 offset:2048
	v_mfma_f32_16x16x32_bf16 v[26:29], v[152:155], v[164:167], v[26:29]
	ds_read_b128 v[114:117], v141 offset:4096
	s_add_u32 m0, s22, 0x8c00
	v_add_u32_e32 v178, 0x8040, v138
	global_load_lds_dwordx4 v178, s[18:19]
	v_mfma_f32_16x16x32_bf16 v[30:33], v[156:159], v[164:167], v[30:33]
	ds_read_b128 v[118:121], v141 offset:6144
	v_mfma_f32_16x16x32_bf16 v[34:37], v[144:147], v[168:171], v[34:37]
	s_add_u32 m0, s22, 0xc000
	v_mov_b32_e32 v177, v139
	global_load_lds_dwordx4 v177, s[20:21]
	v_mfma_f32_16x16x32_bf16 v[38:41], v[148:151], v[168:171], v[38:41]
	v_mfma_f32_16x16x32_bf16 v[42:45], v[152:155], v[168:171], v[42:45]
	s_add_u32 m0, s22, 0xc400
	v_add_u32_e32 v178, 0x40, v139
	global_load_lds_dwordx4 v178, s[20:21]
	v_mfma_f32_16x16x32_bf16 v[46:49], v[156:159], v[168:171], v[46:49]
	v_mfma_f32_16x16x32_bf16 v[50:53], v[144:147], v[172:175], v[50:53]
	s_add_u32 m0, s22, 0xc800
	v_add_u32_e32 v177, 0x8000, v139
	global_load_lds_dwordx4 v177, s[20:21]
	v_mfma_f32_16x16x32_bf16 v[54:57], v[148:151], v[172:175], v[54:57]
	v_mfma_f32_16x16x32_bf16 v[58:61], v[152:155], v[172:175], v[58:61]
	s_add_u32 m0, s22, 0xcc00
	v_add_u32_e32 v178, 0x8040, v139
	global_load_lds_dwordx4 v178, s[20:21]
	v_mfma_f32_16x16x32_bf16 v[62:65], v[156:159], v[172:175], v[62:65]
	v_add_u32_e32 v138, 0x80, v138
	v_add_u32_e32 v139, 0x80, v139
	s_mov_b32 s16, 6
.Lgm_loop:
	s_waitcnt lgkmcnt(0)
	v_mfma_f32_16x16x32_bf16 v[2:5], v[90:93], v[106:109], v[2:5]
	ds_read_b128 v[144:147], v142 offset:1024
	v_mfma_f32_16x16x32_bf16 v[6:9], v[94:97], v[106:109], v[6:9]
	ds_read_b128 v[148:151], v142 offset:3072
	v_mfma_f32_16x16x32_bf16 v[10:13], v[98:101], v[106:109], v[10:13]
	ds_read_b128 v[152:155], v142 offset:5120
	v_mfma_f32_16x16x32_bf16 v[14:17], v[102:105], v[106:109], v[14:17]
	ds_read_b128 v[156:159], v142 offset:7168
	v_mfma_f32_16x16x32_bf16 v[18:21], v[90:93], v[110:113], v[18:21]
	ds_read_b128 v[160:163], v141 offset:1024
	v_mfma_f32_16x16x32_bf16 v[22:25], v[94:97], v[110:113], v[22:25]
	ds_read_b128 v[164:167], v141 offset:3072
	v_mfma_f32_16x16x32_bf16 v[26:29], v[98:101], v[110:113], v[26:29]
	ds_read_b128 v[168:171], v141 offset:5120
	v_mfma_f32_16x16x32_bf16 v[30:33], v[102:105], v[110:113], v[30:33]
	ds_read_b128 v[172:175], v141 offset:7168
	v_mfma_f32_16x16x32_bf16 v[34:37], v[90:93], v[114:117], v[34:37]
	v_mfma_f32_16x16x32_bf16 v[38:41], v[94:97], v[114:117], v[38:41]
	v_mfma_f32_16x16x32_bf16 v[42:45], v[98:101], v[114:117], v[42:45]
	v_mfma_f32_16x16x32_bf16 v[46:49], v[102:105], v[114:117], v[46:49]
	v_mfma_f32_16x16x32_bf16 v[50:53], v[90:93], v[118:121], v[50:53]
	v_mfma_f32_16x16x32_bf16 v[54:57], v[94:97], v[118:121], v[54:57]
	v_mfma_f32_16x16x32_bf16 v[58:61], v[98:101], v[118:121], v[58:61]
	v_mfma_f32_16x16x32_bf16 v[62:65], v[102:105], v[118:121], v[62:65]
	s_waitcnt vmcnt(0) lgkmcnt(0)
	s_barrier
	v_mfma_f32_16x16x32_bf16 v[2:5], v[144:147], v[160:163], v[2:5]
	ds_read_b128 v[90:93], v142 offset:32768
	s_add_u32 m0, s22, 0x0
	v_mov_b32_e32 v177, v138
	global_load_lds_dwordx4 v177, s[18:19]
	v_mfma_f32_16x16x32_bf16 v[6:9], v[148:151], v[160:163], v[6:9]
	ds_read_b128 v[94:97], v142 offset:34816
	v_mfma_f32_16x16x32_bf16 v[10:13], v[152:155], v[160:163], v[10:13]
	ds_read_b128 v[98:101], v142 offset:36864
	s_add_u32 m0, s22, 0x400
	v_add_u32_e32 v178, 0x40, v138
	global_load_lds_dwordx4 v178, s[18:19]
	v_mfma_f32_16x16x32_bf16 v[14:17], v[156:159], v[160:163], v[14:17]
	ds_read_b128 v[102:105], v142 offset:38912
	v_mfma_f32_16x16x32_bf16 v[18:21], v[144:147], v[164:167], v[18:21]
	ds_read_b128 v[106:109], v141 offset:32768
	s_add_u32 m0, s22, 0x800
	v_add_u32_e32 v177, 0x8000, v138
	global_load_lds_dwordx4 v177, s[18:19]
	v_mfma_f32_16x16x32_bf16 v[22:25], v[148:151], v[164:167], v[22:25]
	ds_read_b128 v[110:113], v141 offset:34816
	v_mfma_f32_16x16x32_bf16 v[26:29], v[152:155], v[164:167], v[26:29]
	ds_read_b128 v[114:117], v141 offset:36864
	s_add_u32 m0, s22, 0xc00
	v_add_u32_e32 v178, 0x8040, v138
	global_load_lds_dwordx4 v178, s[18:19]
	v_mfma_f32_16x16x32_bf16 v[30:33], v[156:159], v[164:167], v[30:33]
	ds_read_b128 v[118:121], v141 offset:38912
	v_mfma_f32_16x16x32_bf16 v[34:37], v[144:147], v[168:171], v[34:37]
	s_add_u32 m0, s22, 0x4000
	v_mov_b32_e32 v177, v139
	global_load_lds_dwordx4 v177, s[20:21]
	v_mfma_f32_16x16x32_bf16 v[38:41], v[148:151], v[168:171], v[38:41]
	v_mfma_f32_16x16x32_bf16 v[42:45], v[152:155], v[168:171], v[42:45]
	s_add_u32 m0, s22, 0x4400
	v_add_u32_e32 v178, 0x40, v139
	global_load_lds_dwordx4 v178, s[20:21]
	v_mfma_f32_16x16x32_bf16 v[46:49], v[156:159], v[168:171], v[46:49]
	v_mfma_f32_16x16x32_bf16 v[50:53], v[144:147], v[172:175], v[50:53]
	s_add_u32 m0, s22, 0x4800
	v_add_u32_e32 v177, 0x8000, v139
	global_load_lds_dwordx4 v177, s[20:21]
	v_mfma_f32_16x16x32_bf16 v[54:57], v[148:151], v[172:175], v[54:57]
	v_mfma_f32_16x16x32_bf16 v[58:61], v[152:155], v[172:175], v[58:61]
	s_add_u32 m0, s22, 0x4c00
	v_add_u32_e32 v178, 0x8040, v139
	global_load_lds_dwordx4 v178, s[20:21]
	v_mfma_f32_16x16x32_bf16 v[62:65], v[156:159], v[172:175], v[62:65]
	v_add_u32_e32 v138, 0x80, v138
	v_add_u32_e32 v139, 0x80, v139
	s_waitcnt lgkmcnt(0)
	v_mfma_f32_16x16x32_bf16 v[2:5], v[90:93], v[106:109], v[2:5]
	ds_read_b128 v[144:147], v142 offset:33792
	v_mfma_f32_16x16x32_bf16 v[6:9], v[94:97], v[106:109], v[6:9]
	ds_read_b128 v[148:151], v142 offset:35840
	v_mfma_f32_16x16x32_bf16 v[10:13], v[98:101], v[106:109], v[10:13]
	ds_read_b128 v[152:155], v142 offset:37888
	v_mfma_f32_16x16x32_bf16 v[14:17], v[102:105], v[106:109], v[14:17]
	ds_read_b128 v[156:159], v142 offset:39936
	v_mfma_f32_16x16x32_bf16 v[18:21], v[90:93], v[110:113], v[18:21]
	ds_read_b128 v[160:163], v141 offset:33792
	v_mfma_f32_16x16x32_bf16 v[22:25], v[94:97], v[110:113], v[22:25]
	ds_read_b128 v[164:167], v141 offset:35840
	v_mfma_f32_16x16x32_bf16 v[26:29], v[98:101], v[110:113], v[26:29]
	ds_read_b128 v[168:171], v141 offset:37888
	v_mfma_f32_16x16x32_bf16 v[30:33], v[102:105], v[110:113], v[30:33]
	ds_read_b128 v[172:175], v141 offset:39936
	v_mfma_f32_16x16x32_bf16 v[34:37], v[90:93], v[114:117], v[34:37]
	v_mfma_f32_16x16x32_bf16 v[38:41], v[94:97], v[114:117], v[38:41]
	v_mfma_f32_16x16x32_bf16 v[42:45], v[98:101], v[114:117], v[42:45]
	v_mfma_f32_16x16x32_bf16 v[46:49], v[102:105], v[114:117], v[46:49]
	v_mfma_f32_16x16x32_bf16 v[50:53], v[90:93], v[118:121], v[50:53]
	v_mfma_f32_16x16x32_bf16 v[54:57], v[94:97], v[118:121], v[54:57]
	v_mfma_f32_16x16x32_bf16 v[58:61], v[98:101], v[118:121], v[58:61]
	v_mfma_f32_16x16x32_bf16 v[62:65], v[102:105], v[118:121], v[62:65]
	s_waitcnt vmcnt(0) lgkmcnt(0)
	s_barrier
	v_mfma_f32_16x16x32_bf16 v[2:5], v[144:147], v[160:163], v[2:5]
	ds_read_b128 v[90:93], v142
	s_add_u32 m0, s22, 0x8000
	v_mov_b32_e32 v177, v138
	global_load_lds_dwordx4 v177, s[18:19]
	v_mfma_f32_16x16x32_bf16 v[6:9], v[148:151], v[160:163], v[6:9]
	ds_read_b128 v[94:97], v142 offset:2048
	v_mfma_f32_16x16x32_bf16 v[10:13], v[152:155], v[160:163], v[10:13]
	ds_read_b128 v[98:101], v142 offset:4096
	s_add_u32 m0, s22, 0x8400
	v_add_u32_e32 v178, 0x40, v138
	global_load_lds_dwordx4 v178, s[18:19]
	v_mfma_f32_16x16x32_bf16 v[14:17], v[156:159], v[160:163], v[14:17]
	ds_read_b128 v[102:105], v142 offset:6144
	v_mfma_f32_16x16x32_bf16 v[18:21], v[144:147], v[164:167], v[18:21]
	ds_read_b128 v[106:109], v141
	s_add_u32 m0, s22, 0x8800
	v_add_u32_e32 v177, 0x8000, v138
	global_load_lds_dwordx4 v177, s[18:19]
	v_mfma_f32_16x16x32_bf16 v[22:25], v[148:151], v[164:167], v[22:25]
	ds_read_b128 v[110:113], v141 offset:2048
	v_mfma_f32_16x16x32_bf16 v[26:29], v[152:155], v[164:167], v[26:29]
	ds_read_b128 v[114:117], v141 offset:4096
	s_add_u32 m0, s22, 0x8c00
	v_add_u32_e32 v178, 0x8040, v138
	global_load_lds_dwordx4 v178, s[18:19]
	v_mfma_f32_16x16x32_bf16 v[30:33], v[156:159], v[164:167], v[30:33]
	ds_read_b128 v[118:121], v141 offset:6144
	v_mfma_f32_16x16x32_bf16 v[34:37], v[144:147], v[168:171], v[34:37]
	s_add_u32 m0, s22, 0xc000
	v_mov_b32_e32 v177, v139
	global_load_lds_dwordx4 v177, s[20:21]
	v_mfma_f32_16x16x32_bf16 v[38:41], v[148:151], v[168:171], v[38:41]
	v_mfma_f32_16x16x32_bf16 v[42:45], v[152:155], v[168:171], v[42:45]
	s_add_u32 m0, s22, 0xc400
	v_add_u32_e32 v178, 0x40, v139
	global_load_lds_dwordx4 v178, s[20:21]
	v_mfma_f32_16x16x32_bf16 v[46:49], v[156:159], v[168:171], v[46:49]
	v_mfma_f32_16x16x32_bf16 v[50:53], v[144:147], v[172:175], v[50:53]
	s_add_u32 m0, s22, 0xc800
	v_add_u32_e32 v177, 0x8000, v139
	global_load_lds_dwordx4 v177, s[20:21]
	v_mfma_f32_16x16x32_bf16 v[54:57], v[148:151], v[172:175], v[54:57]
	v_mfma_f32_16x16x32_bf16 v[58:61], v[152:155], v[172:175], v[58:61]
	s_add_u32 m0, s22, 0xcc00
	v_add_u32_e32 v178, 0x8040, v139
	global_load_lds_dwordx4 v178, s[20:21]
	v_mfma_f32_16x16x32_bf16 v[62:65], v[156:159], v[172:175], v[62:65]
	v_add_u32_e32 v138, 0x80, v138
	v_add_u32_e32 v139, 0x80, v139
	s_sub_u32 s16, s16, 1
	s_cmp_lg_u32 s16, 0
	s_cbranch_scc1 .Lgm_loop
	s_lshl_b32 s3, s26, 12
	v_add_u32_e32 v195, s3, v176
	global_load_dwordx4 v[240:243], v195, s[24:25]
	global_load_dwordx4 v[244:247], v195, s[24:25] offset:64
	global_load_dwordx4 v[248:251], v195, s[24:25] offset:128
	global_load_dwordx4 v[252:255], v195, s[24:25] offset:192
	s_cmp_eq_u32 s26, 3
	s_cbranch_scc1 .Lgm_lastbr
	v_add_u32_e32 v137, 0x7fe00, v137
	s_mov_b32 s27, 1
	s_branch .Lgm_tail

.Lgm_tail:
	s_waitcnt lgkmcnt(0)
	v_mfma_f32_16x16x32_bf16 v[2:5], v[90:93], v[106:109], v[2:5]
	ds_read_b128 v[144:147], v142 offset:1024
	v_mfma_f32_16x16x32_bf16 v[6:9], v[94:97], v[106:109], v[6:9]
	ds_read_b128 v[148:151], v142 offset:3072
	v_mfma_f32_16x16x32_bf16 v[10:13], v[98:101], v[106:109], v[10:13]
	ds_read_b128 v[152:155], v142 offset:5120
	v_mfma_f32_16x16x32_bf16 v[14:17], v[102:105], v[106:109], v[14:17]
	ds_read_b128 v[156:159], v142 offset:7168
	v_mfma_f32_16x16x32_bf16 v[18:21], v[90:93], v[110:113], v[18:21]
	ds_read_b128 v[160:163], v141 offset:1024
	v_mfma_f32_16x16x32_bf16 v[22:25], v[94:97], v[110:113], v[22:25]
	ds_read_b128 v[164:167], v141 offset:3072
	v_mfma_f32_16x16x32_bf16 v[26:29], v[98:101], v[110:113], v[26:29]
	ds_read_b128 v[168:171], v141 offset:5120
	v_mfma_f32_16x16x32_bf16 v[30:33], v[102:105], v[110:113], v[30:33]
	ds_read_b128 v[172:175], v141 offset:7168
	v_mfma_f32_16x16x32_bf16 v[34:37], v[90:93], v[114:117], v[34:37]
	v_mfma_f32_16x16x32_bf16 v[38:41], v[94:97], v[114:117], v[38:41]
	v_mfma_f32_16x16x32_bf16 v[42:45], v[98:101], v[114:117], v[42:45]
	v_mfma_f32_16x16x32_bf16 v[46:49], v[102:105], v[114:117], v[46:49]
	v_mfma_f32_16x16x32_bf16 v[50:53], v[90:93], v[118:121], v[50:53]
	v_mfma_f32_16x16x32_bf16 v[54:57], v[94:97], v[118:121], v[54:57]
	v_mfma_f32_16x16x32_bf16 v[58:61], v[98:101], v[118:121], v[58:61]
	v_mfma_f32_16x16x32_bf16 v[62:65], v[102:105], v[118:121], v[62:65]
	s_waitcnt vmcnt(0) lgkmcnt(0)
	s_barrier
	v_mfma_f32_16x16x32_bf16 v[2:5], v[144:147], v[160:163], v[2:5]
	ds_read_b128 v[90:93], v142 offset:32768
	s_add_u32 m0, s22, 0x0
	v_mov_b32_e32 v177, v136
	global_load_lds_dwordx4 v177, s[6:7]
	v_mfma_f32_16x16x32_bf16 v[6:9], v[148:151], v[160:163], v[6:9]
	ds_read_b128 v[94:97], v142 offset:34816
	v_mfma_f32_16x16x32_bf16 v[10:13], v[152:155], v[160:163], v[10:13]
	ds_read_b128 v[98:101], v142 offset:36864
	s_add_u32 m0, s22, 0x400
	v_add_u32_e32 v178, 0x40, v136
	global_load_lds_dwordx4 v178, s[6:7]
	v_mfma_f32_16x16x32_bf16 v[14:17], v[156:159], v[160:163], v[14:17]
	ds_read_b128 v[102:105], v142 offset:38912
	v_mfma_f32_16x16x32_bf16 v[18:21], v[144:147], v[164:167], v[18:21]
	ds_read_b128 v[106:109], v141 offset:32768
	s_add_u32 m0, s22, 0x800
	v_add_u32_e32 v177, 0x8000, v136
	global_load_lds_dwordx4 v177, s[6:7]
	v_mfma_f32_16x16x32_bf16 v[22:25], v[148:151], v[164:167], v[22:25]
	ds_read_b128 v[110:113], v141 offset:34816
	v_mfma_f32_16x16x32_bf16 v[26:29], v[152:155], v[164:167], v[26:29]
	ds_read_b128 v[114:117], v141 offset:36864
	s_add_u32 m0, s22, 0xc00
	v_add_u32_e32 v178, 0x8040, v136
	global_load_lds_dwordx4 v178, s[6:7]
	v_mfma_f32_16x16x32_bf16 v[30:33], v[156:159], v[164:167], v[30:33]
	ds_read_b128 v[118:121], v141 offset:38912
	v_mfma_f32_16x16x32_bf16 v[34:37], v[144:147], v[168:171], v[34:37]
	s_add_u32 m0, s22, 0x4000
	v_mov_b32_e32 v177, v137
	global_load_lds_dwordx4 v177, s[8:9]
	v_mfma_f32_16x16x32_bf16 v[38:41], v[148:151], v[168:171], v[38:41]
	v_mfma_f32_16x16x32_bf16 v[42:45], v[152:155], v[168:171], v[42:45]
	s_add_u32 m0, s22, 0x4400
	v_add_u32_e32 v178, 0x40, v137
	global_load_lds_dwordx4 v178, s[8:9]
	v_mfma_f32_16x16x32_bf16 v[46:49], v[156:159], v[168:171], v[46:49]
	v_mfma_f32_16x16x32_bf16 v[50:53], v[144:147], v[172:175], v[50:53]
	s_add_u32 m0, s22, 0x4800
	v_add_u32_e32 v177, 0x2000, v137
	global_load_lds_dwordx4 v177, s[8:9]
	v_mfma_f32_16x16x32_bf16 v[54:57], v[148:151], v[172:175], v[54:57]
	v_mfma_f32_16x16x32_bf16 v[58:61], v[152:155], v[172:175], v[58:61]
	s_add_u32 m0, s22, 0x4c00
	v_add_u32_e32 v178, 0x2040, v137
	global_load_lds_dwordx4 v178, s[8:9]
	v_mfma_f32_16x16x32_bf16 v[62:65], v[156:159], v[172:175], v[62:65]
	v_add_u32_e32 v136, 0x80, v136
	v_add_u32_e32 v137, 0x80, v137
	s_waitcnt lgkmcnt(0)
	v_mfma_f32_16x16x32_bf16 v[2:5], v[90:93], v[106:109], v[2:5]
	ds_read_b128 v[144:147], v142 offset:33792
	v_mfma_f32_16x16x32_bf16 v[6:9], v[94:97], v[106:109], v[6:9]
	ds_read_b128 v[148:151], v142 offset:35840
	v_mfma_f32_16x16x32_bf16 v[10:13], v[98:101], v[106:109], v[10:13]
	ds_read_b128 v[152:155], v142 offset:37888
	v_mfma_f32_16x16x32_bf16 v[14:17], v[102:105], v[106:109], v[14:17]
	ds_read_b128 v[156:159], v142 offset:39936
	v_mfma_f32_16x16x32_bf16 v[18:21], v[90:93], v[110:113], v[18:21]
	ds_read_b128 v[160:163], v141 offset:33792
	v_mfma_f32_16x16x32_bf16 v[22:25], v[94:97], v[110:113], v[22:25]
	ds_read_b128 v[164:167], v141 offset:35840
	v_mfma_f32_16x16x32_bf16 v[26:29], v[98:101], v[110:113], v[26:29]
	ds_read_b128 v[168:171], v141 offset:37888
	v_mfma_f32_16x16x32_bf16 v[30:33], v[102:105], v[110:113], v[30:33]
	ds_read_b128 v[172:175], v141 offset:39936
	v_mfma_f32_16x16x32_bf16 v[34:37], v[90:93], v[114:117], v[34:37]
	v_mfma_f32_16x16x32_bf16 v[38:41], v[94:97], v[114:117], v[38:41]
	v_mfma_f32_16x16x32_bf16 v[42:45], v[98:101], v[114:117], v[42:45]
	v_mfma_f32_16x16x32_bf16 v[46:49], v[102:105], v[114:117], v[46:49]
	v_mfma_f32_16x16x32_bf16 v[50:53], v[90:93], v[118:121], v[50:53]
	v_mfma_f32_16x16x32_bf16 v[54:57], v[94:97], v[118:121], v[54:57]
	v_mfma_f32_16x16x32_bf16 v[58:61], v[98:101], v[118:121], v[58:61]
	v_mfma_f32_16x16x32_bf16 v[62:65], v[102:105], v[118:121], v[62:65]
	s_waitcnt vmcnt(0) lgkmcnt(0)
	s_barrier
	v_mfma_f32_16x16x32_bf16 v[2:5], v[144:147], v[160:163], v[2:5]
	ds_read_b128 v[90:93], v142
	s_add_u32 m0, s22, 0x8000
	v_mov_b32_e32 v177, v136
	global_load_lds_dwordx4 v177, s[6:7]
	v_mfma_f32_16x16x32_bf16 v[6:9], v[148:151], v[160:163], v[6:9]
	ds_read_b128 v[94:97], v142 offset:2048
	v_mfma_f32_16x16x32_bf16 v[10:13], v[152:155], v[160:163], v[10:13]
	ds_read_b128 v[98:101], v142 offset:4096
	s_add_u32 m0, s22, 0x8400
	v_add_u32_e32 v178, 0x40, v136
	global_load_lds_dwordx4 v178, s[6:7]
	v_mfma_f32_16x16x32_bf16 v[14:17], v[156:159], v[160:163], v[14:17]
	ds_read_b128 v[102:105], v142 offset:6144
	v_mfma_f32_16x16x32_bf16 v[18:21], v[144:147], v[164:167], v[18:21]
	ds_read_b128 v[106:109], v141
	s_add_u32 m0, s22, 0x8800
	v_add_u32_e32 v177, 0x8000, v136
	global_load_lds_dwordx4 v177, s[6:7]
	v_mfma_f32_16x16x32_bf16 v[22:25], v[148:151], v[164:167], v[22:25]
	ds_read_b128 v[110:113], v141 offset:2048
	v_mfma_f32_16x16x32_bf16 v[26:29], v[152:155], v[164:167], v[26:29]
	ds_read_b128 v[114:117], v141 offset:4096
	s_add_u32 m0, s22, 0x8c00
	v_add_u32_e32 v178, 0x8040, v136
	global_load_lds_dwordx4 v178, s[6:7]
	v_mfma_f32_16x16x32_bf16 v[30:33], v[156:159], v[164:167], v[30:33]
	ds_read_b128 v[118:121], v141 offset:6144
	v_mfma_f32_16x16x32_bf16 v[34:37], v[144:147], v[168:171], v[34:37]
	s_add_u32 m0, s22, 0xc000
	v_mov_b32_e32 v177, v137
	global_load_lds_dwordx4 v177, s[8:9]
	v_mfma_f32_16x16x32_bf16 v[38:41], v[148:151], v[168:171], v[38:41]
	v_mfma_f32_16x16x32_bf16 v[42:45], v[152:155], v[168:171], v[42:45]
	s_add_u32 m0, s22, 0xc400
	v_add_u32_e32 v178, 0x40, v137
	global_load_lds_dwordx4 v178, s[8:9]
	v_mfma_f32_16x16x32_bf16 v[46:49], v[156:159], v[168:171], v[46:49]
	v_mfma_f32_16x16x32_bf16 v[50:53], v[144:147], v[172:175], v[50:53]
	s_add_u32 m0, s22, 0xc800
	v_add_u32_e32 v177, 0x2000, v137
	global_load_lds_dwordx4 v177, s[8:9]
	v_mfma_f32_16x16x32_bf16 v[54:57], v[148:151], v[172:175], v[54:57]
	v_mfma_f32_16x16x32_bf16 v[58:61], v[152:155], v[172:175], v[58:61]
	s_add_u32 m0, s22, 0xcc00
	v_add_u32_e32 v178, 0x2040, v137
	global_load_lds_dwordx4 v178, s[8:9]
	v_mfma_f32_16x16x32_bf16 v[62:65], v[156:159], v[172:175], v[62:65]
	v_add_u32_e32 v136, 0x80, v136
	v_add_u32_e32 v137, 0x80, v137
	s_branch .Lgm_mrg
